# P0 weight transposes: the 8 gain loads of an item issued together ahead of its weight loads with one wait (was: load + vmcnt(0) before every weight load, draining the loads in flight); on top of v133
# speedup vs baseline: 1.0174x; 1.0069x over previous
.LBB0_35:
	s_lshr_b32 s26, s50, 5
	v_cvt_f32_u32_e32 v64, s26
	s_sub_i32 s43, 0, s26
	s_abs_i32 s42, s48
	s_ashr_i32 s27, s48, 31
	v_rcp_iflag_f32_e32 v64, v64
	s_nop 0
	v_mul_f32_e32 v64, 0x4f7ffffe, v64
	v_cvt_u32_f32_e32 v64, v64
	s_nop 0
	v_readfirstlane_b32 s49, v64
	s_mul_i32 s43, s43, s49
	s_mul_hi_u32 s43, s49, s43
	s_add_i32 s49, s49, s43
	s_mul_hi_u32 s43, s42, s49
	s_mul_i32 s49, s43, s26
	s_sub_i32 s42, s42, s49
	s_add_i32 s51, s43, 1
	s_sub_i32 s49, s42, s26
	s_cmp_ge_u32 s42, s26
	s_cselect_b32 s43, s51, s43
	s_cselect_b32 s42, s49, s42
	s_add_i32 s49, s43, 1
	s_cmp_ge_u32 s42, s26
	s_cselect_b32 s42, s49, s43
	s_xor_b32 s42, s42, s27
	s_sub_i32 s27, s42, s27
	s_mul_i32 s26, s27, s26
	s_sub_i32 s43, s48, s26
	s_lshl_b32 s42, s27, 6
	s_and_b32 s26, s43, -16
	s_cmp_eq_u32 s26, 16
	s_cselect_b64 s[48:49], -1, 0
	v_or_b32_e32 v92, s42, v105
	s_and_b64 vcc, s[0:1], s[48:49]
	v_cndmask_b32_e32 v102, 1.0, v115, vcc
	s_cmp_lg_u64 s[44:45], 0
	v_ashrrev_i32_e32 v93, 31, v92
	s_cselect_b64 s[48:49], -1, 0
	s_cmp_eq_u64 s[44:45], 0
	v_lshl_add_u64 v[94:95], v[92:93], 2, s[44:45]
	v_mov_b32_e32 v100, v102
	s_cbranch_scc1 .Lgh0_skip
	global_load_dword v140, v[94:95], off
	global_load_dword v141, v[94:95], off offset:32
	global_load_dword v142, v[94:95], off offset:64
	global_load_dword v143, v[94:95], off offset:96
	global_load_dword v144, v[94:95], off offset:128
	global_load_dword v145, v[94:95], off offset:160
	global_load_dword v146, v[94:95], off offset:192
	global_load_dword v147, v[94:95], off offset:224
.Lgh0_skip:
	s_cbranch_scc1 .LBB0_37
	s_waitcnt vmcnt(0)
	v_mul_f32_e32 v100, v102, v140
.LBB0_37:
	v_mad_u64_u32 v[64:65], s[0:1], v92, s50, 0
	v_mov_b32_e32 v66, v65
	v_mad_u64_u32 v[66:67], s[0:1], v93, s50, v[66:67]
	s_lshl_b32 s44, s43, 5
	v_mov_b32_e32 v65, v66
	s_ashr_i32 s45, s44, 31
	v_lshl_add_u64 v[64:65], v[64:65], 2, s[46:47]
	v_lshl_add_u64 v[64:65], s[44:45], 2, v[64:65]
	v_lshl_add_u64 v[64:65], v[64:65], 0, v[96:97]
	global_load_dwordx4 v[64:67], v[64:65], off nt
	v_cndmask_b32_e64 v68, 0, 1, s[48:49]
	v_cmp_ne_u32_e64 s[0:1], 1, v68
	s_andn2_b64 vcc, exec, s[48:49]
	v_mov_b32_e32 v104, v102
	s_cbranch_vccnz .LBB0_39
	v_mul_f32_e32 v104, v102, v141
.LBB0_39:
	v_or_b32_e32 v68, 8, v92
	v_mad_u64_u32 v[68:69], s[48:49], v68, s50, 0
	v_mov_b32_e32 v70, v69
	v_mad_u64_u32 v[70:71], s[48:49], v93, s50, v[70:71]
	v_mov_b32_e32 v69, v70
	v_lshl_add_u64 v[68:69], v[68:69], 2, s[46:47]
	v_lshl_add_u64 v[68:69], s[44:45], 2, v[68:69]
	v_lshl_add_u64 v[68:69], v[68:69], 0, v[96:97]
	global_load_dwordx4 v[68:71], v[68:69], off nt
	s_and_b64 vcc, exec, s[0:1]
	v_mov_b32_e32 v106, v102
	s_cbranch_vccnz .LBB0_41
	v_mul_f32_e32 v106, v102, v142
.LBB0_41:
	v_or_b32_e32 v72, 16, v92
	v_mad_u64_u32 v[72:73], s[48:49], v72, s50, 0
	v_mov_b32_e32 v74, v73
	v_mad_u64_u32 v[74:75], s[48:49], v93, s50, v[74:75]
	v_mov_b32_e32 v73, v74
	v_lshl_add_u64 v[72:73], v[72:73], 2, s[46:47]
	v_lshl_add_u64 v[72:73], s[44:45], 2, v[72:73]
	v_lshl_add_u64 v[72:73], v[72:73], 0, v[96:97]
	global_load_dwordx4 v[72:75], v[72:73], off nt
	s_and_b64 vcc, exec, s[0:1]
	v_mov_b32_e32 v108, v102
	s_cbranch_vccnz .LBB0_43
	v_mul_f32_e32 v108, v102, v143
.LBB0_43:
	v_or_b32_e32 v76, 24, v92
	v_mad_u64_u32 v[76:77], s[48:49], v76, s50, 0
	v_mov_b32_e32 v78, v77
	v_mad_u64_u32 v[78:79], s[48:49], v93, s50, v[78:79]
	v_mov_b32_e32 v77, v78
	v_lshl_add_u64 v[76:77], v[76:77], 2, s[46:47]
	v_lshl_add_u64 v[76:77], s[44:45], 2, v[76:77]
	v_lshl_add_u64 v[76:77], v[76:77], 0, v[96:97]
	global_load_dwordx4 v[76:79], v[76:77], off nt
	s_and_b64 vcc, exec, s[0:1]
	v_mov_b32_e32 v110, v102
	s_cbranch_vccnz .LBB0_45
	v_mul_f32_e32 v110, v102, v144
.LBB0_45:
	v_or_b32_e32 v80, 32, v92
	v_mad_u64_u32 v[80:81], s[48:49], v80, s50, 0
	v_mov_b32_e32 v82, v81
	v_mad_u64_u32 v[82:83], s[48:49], v93, s50, v[82:83]
	v_mov_b32_e32 v81, v82
	v_lshl_add_u64 v[80:81], v[80:81], 2, s[46:47]
	v_lshl_add_u64 v[80:81], s[44:45], 2, v[80:81]
	v_lshl_add_u64 v[80:81], v[80:81], 0, v[96:97]
	global_load_dwordx4 v[80:83], v[80:81], off nt
	s_and_b64 vcc, exec, s[0:1]
	v_mov_b32_e32 v112, v102
	s_cbranch_vccnz .LBB0_47
	v_mul_f32_e32 v112, v102, v145
.LBB0_47:
	v_or_b32_e32 v84, 40, v92
	v_mad_u64_u32 v[84:85], s[48:49], v84, s50, 0
	v_mov_b32_e32 v86, v85
	v_mad_u64_u32 v[86:87], s[48:49], v93, s50, v[86:87]
	v_mov_b32_e32 v85, v86
	v_lshl_add_u64 v[84:85], v[84:85], 2, s[46:47]
	v_lshl_add_u64 v[84:85], s[44:45], 2, v[84:85]
	v_lshl_add_u64 v[84:85], v[84:85], 0, v[96:97]
	global_load_dwordx4 v[84:87], v[84:85], off nt
	s_and_b64 vcc, exec, s[0:1]
	v_mov_b32_e32 v114, v102
	s_cbranch_vccnz .LBB0_49
	v_mul_f32_e32 v114, v102, v146
.LBB0_49:
	v_or_b32_e32 v88, 48, v92
	v_mad_u64_u32 v[88:89], s[48:49], v88, s50, 0
	v_mov_b32_e32 v90, v89
	v_mad_u64_u32 v[90:91], s[48:49], v93, s50, v[90:91]
	v_mov_b32_e32 v89, v90
	v_lshl_add_u64 v[88:89], v[88:89], 2, s[46:47]
	v_lshl_add_u64 v[88:89], s[44:45], 2, v[88:89]
	v_lshl_add_u64 v[88:89], v[88:89], 0, v[96:97]
	global_load_dwordx4 v[88:91], v[88:89], off nt
	s_and_b64 vcc, exec, s[0:1]
	s_cbranch_vccnz .LBB0_51
	v_mul_f32_e32 v102, v102, v147

.LBB0_66:
	s_lshr_b32 s26, s57, 5
	v_cvt_f32_u32_e32 v0, s26
	s_sub_i32 s53, 0, s26
	s_abs_i32 s52, s37
	s_ashr_i32 s27, s37, 31
	v_rcp_iflag_f32_e32 v0, v0
	s_nop 0
	v_mul_f32_e32 v0, 0x4f7ffffe, v0
	v_cvt_u32_f32_e32 v0, v0
	s_nop 0
	v_readfirstlane_b32 s54, v0
	s_mul_i32 s53, s53, s54
	s_mul_hi_u32 s53, s54, s53
	s_add_i32 s54, s54, s53
	s_mul_hi_u32 s53, s52, s54
	s_mul_i32 s54, s53, s26
	s_sub_i32 s52, s52, s54
	s_add_i32 s55, s53, 1
	s_sub_i32 s54, s52, s26
	s_cmp_ge_u32 s52, s26
	s_cselect_b32 s53, s55, s53
	s_cselect_b32 s52, s54, s52
	s_add_i32 s54, s53, 1
	s_cmp_ge_u32 s52, s26
	s_cselect_b32 s52, s54, s53
	s_xor_b32 s52, s52, s27
	s_sub_i32 s27, s52, s27
	s_mul_i32 s26, s27, s26
	s_sub_i32 s54, s37, s26
	s_and_b32 s26, s54, -16
	s_cmp_eq_u32 s26, 16
	s_cselect_b64 s[52:53], -1, 0
	v_lshl_or_b32 v46, s27, 6, v105
	s_and_b64 vcc, s[0:1], s[52:53]
	v_ashrrev_i32_e32 v47, 31, v46
	v_cndmask_b32_e32 v116, 1.0, v115, vcc
	s_cmp_lg_u64 s[50:51], 0
	s_cselect_b64 s[52:53], -1, 0
	s_cmp_eq_u64 s[50:51], 0
	v_lshl_add_u64 v[124:125], v[46:47], 2, s[50:51]
	v_mov_b32_e32 v44, v116
	s_cbranch_scc1 .Lgh1_skip
	global_load_dword v148, v[124:125], off
	global_load_dword v149, v[124:125], off offset:32
	global_load_dword v150, v[124:125], off offset:64
	global_load_dword v151, v[124:125], off offset:96
	global_load_dword v152, v[124:125], off offset:128
	global_load_dword v153, v[124:125], off offset:160
	global_load_dword v154, v[124:125], off offset:192
	global_load_dword v155, v[124:125], off offset:224
.Lgh1_skip:
	s_cbranch_scc1 .LBB0_68
	s_waitcnt vmcnt(0)
	v_mul_f32_e32 v44, v116, v148
.LBB0_68:
	v_mad_u64_u32 v[0:1], s[0:1], v46, s57, 0
	v_mov_b32_e32 v2, v1
	v_mad_u64_u32 v[2:3], s[0:1], v47, s57, v[2:3]
	s_lshl_b32 s50, s54, 5
	v_mov_b32_e32 v1, v2
	s_ashr_i32 s51, s50, 31
	v_lshl_add_u64 v[0:1], v[0:1], 2, s[48:49]
	v_lshl_add_u64 v[0:1], s[50:51], 2, v[0:1]
	v_lshl_add_u64 v[0:1], v[0:1], 0, v[96:97]
	global_load_dwordx4 v[36:39], v[0:1], off nt
	v_cndmask_b32_e64 v0, 0, 1, s[52:53]
	v_cmp_ne_u32_e64 s[0:1], 1, v0
	s_andn2_b64 vcc, exec, s[52:53]
	v_mov_b32_e32 v118, v116
	s_cbranch_vccnz .LBB0_70
	v_mul_f32_e32 v118, v116, v149
.LBB0_70:
	v_or_b32_e32 v0, 8, v46
	v_mad_u64_u32 v[0:1], s[52:53], v0, s57, 0
	v_mov_b32_e32 v2, v1
	v_mad_u64_u32 v[2:3], s[52:53], v47, s57, v[2:3]
	v_mov_b32_e32 v1, v2
	v_lshl_add_u64 v[0:1], v[0:1], 2, s[48:49]
	v_lshl_add_u64 v[0:1], s[50:51], 2, v[0:1]
	v_lshl_add_u64 v[0:1], v[0:1], 0, v[96:97]
	global_load_dwordx4 v[32:35], v[0:1], off nt
	s_and_b64 vcc, exec, s[0:1]
	v_mov_b32_e32 v120, v116
	s_cbranch_vccnz .LBB0_72
	v_mul_f32_e32 v120, v116, v150
.LBB0_72:
	v_or_b32_e32 v0, 16, v46
	v_mad_u64_u32 v[0:1], s[52:53], v0, s57, 0
	v_mov_b32_e32 v2, v1
	v_mad_u64_u32 v[2:3], s[52:53], v47, s57, v[2:3]
	v_mov_b32_e32 v1, v2
	v_lshl_add_u64 v[0:1], v[0:1], 2, s[48:49]
	v_lshl_add_u64 v[0:1], s[50:51], 2, v[0:1]
	v_lshl_add_u64 v[0:1], v[0:1], 0, v[96:97]
	global_load_dwordx4 v[24:27], v[0:1], off nt
	s_and_b64 vcc, exec, s[0:1]
	v_mov_b32_e32 v122, v116
	s_cbranch_vccnz .LBB0_74
	v_mul_f32_e32 v122, v116, v151
.LBB0_74:
	v_or_b32_e32 v0, 24, v46
	v_mad_u64_u32 v[0:1], s[52:53], v0, s57, 0
	v_mov_b32_e32 v2, v1
	v_mad_u64_u32 v[2:3], s[52:53], v47, s57, v[2:3]
	v_mov_b32_e32 v1, v2
	v_lshl_add_u64 v[0:1], v[0:1], 2, s[48:49]
	v_lshl_add_u64 v[0:1], s[50:51], 2, v[0:1]
	v_lshl_add_u64 v[0:1], v[0:1], 0, v[96:97]
	global_load_dwordx4 v[16:19], v[0:1], off nt
	s_and_b64 vcc, exec, s[0:1]
	v_mov_b32_e32 v126, v116
	s_cbranch_vccnz .LBB0_76
	v_mul_f32_e32 v126, v116, v152
.LBB0_76:
	v_or_b32_e32 v0, 32, v46
	v_mad_u64_u32 v[0:1], s[52:53], v0, s57, 0
	v_mov_b32_e32 v2, v1
	v_mad_u64_u32 v[2:3], s[52:53], v47, s57, v[2:3]
	v_mov_b32_e32 v1, v2
	v_lshl_add_u64 v[0:1], v[0:1], 2, s[48:49]
	v_lshl_add_u64 v[0:1], s[50:51], 2, v[0:1]
	v_lshl_add_u64 v[0:1], v[0:1], 0, v[96:97]
	global_load_dwordx4 v[8:11], v[0:1], off nt
	s_and_b64 vcc, exec, s[0:1]
	v_mov_b32_e32 v128, v116
	s_cbranch_vccnz .LBB0_78
	v_mul_f32_e32 v128, v116, v153
.LBB0_78:
	v_or_b32_e32 v0, 40, v46
	v_mad_u64_u32 v[0:1], s[52:53], v0, s57, 0
	v_mov_b32_e32 v2, v1
	v_mad_u64_u32 v[2:3], s[52:53], v47, s57, v[2:3]
	v_mov_b32_e32 v1, v2
	v_lshl_add_u64 v[0:1], v[0:1], 2, s[48:49]
	v_lshl_add_u64 v[0:1], s[50:51], 2, v[0:1]
	v_lshl_add_u64 v[0:1], v[0:1], 0, v[96:97]
	global_load_dwordx4 v[4:7], v[0:1], off nt
	s_and_b64 vcc, exec, s[0:1]
	v_mov_b32_e32 v130, v116
	s_cbranch_vccnz .LBB0_80
	v_mul_f32_e32 v130, v116, v154
.LBB0_80:
	v_or_b32_e32 v0, 48, v46
	v_mad_u64_u32 v[0:1], s[52:53], v0, s57, 0
	v_mov_b32_e32 v2, v1
	v_mad_u64_u32 v[2:3], s[52:53], v47, s57, v[2:3]
	v_mov_b32_e32 v1, v2
	v_lshl_add_u64 v[0:1], v[0:1], 2, s[48:49]
	v_lshl_add_u64 v[0:1], s[50:51], 2, v[0:1]
	v_lshl_add_u64 v[0:1], v[0:1], 0, v[96:97]
	global_load_dwordx4 v[0:3], v[0:1], off nt
	s_and_b64 vcc, exec, s[0:1]
	s_cbranch_vccnz .LBB0_82
	v_mul_f32_e32 v116, v116, v155

.LBB0_96:
	s_lshr_b32 s26, s59, 5
	v_cvt_f32_u32_e32 v12, s26
	s_sub_i32 s54, 0, s26
	s_abs_i32 s45, s56
	s_ashr_i32 s27, s56, 31
	v_rcp_iflag_f32_e32 v12, v12
	s_nop 0
	v_mul_f32_e32 v12, 0x4f7ffffe, v12
	v_cvt_u32_f32_e32 v12, v12
	s_nop 0
	v_readfirstlane_b32 s55, v12
	s_mul_i32 s54, s54, s55
	s_mul_hi_u32 s54, s55, s54
	s_add_i32 s55, s55, s54
	s_mul_hi_u32 s54, s45, s55
	s_mul_i32 s55, s54, s26
	s_sub_i32 s45, s45, s55
	s_add_i32 s64, s54, 1
	s_sub_i32 s55, s45, s26
	s_cmp_ge_u32 s45, s26
	s_cselect_b32 s54, s64, s54
	s_cselect_b32 s45, s55, s45
	s_add_i32 s55, s54, 1
	s_cmp_ge_u32 s45, s26
	s_cselect_b32 s45, s55, s54
	s_xor_b32 s45, s45, s27
	s_sub_i32 s27, s45, s27
	s_mul_i32 s26, s27, s26
	s_sub_i32 s45, s56, s26
	s_and_b32 s26, s45, -16
	s_cmp_eq_u32 s26, 16
	s_cselect_b64 s[54:55], -1, 0
	v_lshl_or_b32 v62, s27, 6, v105
	s_and_b64 vcc, s[0:1], s[54:55]
	v_ashrrev_i32_e32 v63, 31, v62
	v_cndmask_b32_e32 v116, 1.0, v115, vcc
	s_cmp_lg_u64 s[52:53], 0
	s_cselect_b64 s[54:55], -1, 0
	s_cmp_eq_u64 s[52:53], 0
	v_lshl_add_u64 v[124:125], v[62:63], 2, s[52:53]
	v_mov_b32_e32 v60, v116
	s_cbranch_scc1 .Lgh2_skip
	global_load_dword v156, v[124:125], off
	global_load_dword v157, v[124:125], off offset:32
	global_load_dword v158, v[124:125], off offset:64
	global_load_dword v159, v[124:125], off offset:96
	global_load_dword v160, v[124:125], off offset:128
	global_load_dword v161, v[124:125], off offset:160
	global_load_dword v162, v[124:125], off offset:192
	global_load_dword v163, v[124:125], off offset:224
.Lgh2_skip:
	s_cbranch_scc1 .LBB0_98
	s_waitcnt vmcnt(0)
	v_mul_f32_e32 v60, v116, v156
.LBB0_98:
	v_mad_u64_u32 v[12:13], s[0:1], v62, s59, 0
	v_mov_b32_e32 v14, v13
	v_mad_u64_u32 v[14:15], s[0:1], v63, s59, v[14:15]
	s_lshl_b32 s52, s45, 5
	v_mov_b32_e32 v13, v14
	s_ashr_i32 s53, s52, 31
	v_lshl_add_u64 v[12:13], v[12:13], 2, s[50:51]
	v_lshl_add_u64 v[12:13], s[52:53], 2, v[12:13]
	v_lshl_add_u64 v[12:13], v[12:13], 0, v[96:97]
	global_load_dwordx4 v[56:59], v[12:13], off nt
	v_cndmask_b32_e64 v12, 0, 1, s[54:55]
	v_cmp_ne_u32_e64 s[0:1], 1, v12
	s_andn2_b64 vcc, exec, s[54:55]
	v_mov_b32_e32 v118, v116
	s_cbranch_vccnz .LBB0_100
	v_mul_f32_e32 v118, v116, v157
.LBB0_100:
	v_or_b32_e32 v12, 8, v62
	v_mad_u64_u32 v[12:13], s[54:55], v12, s59, 0
	v_mov_b32_e32 v14, v13
	v_mad_u64_u32 v[14:15], s[54:55], v63, s59, v[14:15]
	v_mov_b32_e32 v13, v14
	v_lshl_add_u64 v[12:13], v[12:13], 2, s[50:51]
	v_lshl_add_u64 v[12:13], s[52:53], 2, v[12:13]
	v_lshl_add_u64 v[12:13], v[12:13], 0, v[96:97]
	global_load_dwordx4 v[52:55], v[12:13], off nt
	s_and_b64 vcc, exec, s[0:1]
	v_mov_b32_e32 v120, v116
	s_cbranch_vccnz .LBB0_102
	v_mul_f32_e32 v120, v116, v158
.LBB0_102:
	v_or_b32_e32 v12, 16, v62
	v_mad_u64_u32 v[12:13], s[54:55], v12, s59, 0
	v_mov_b32_e32 v14, v13
	v_mad_u64_u32 v[14:15], s[54:55], v63, s59, v[14:15]
	v_mov_b32_e32 v13, v14
	v_lshl_add_u64 v[12:13], v[12:13], 2, s[50:51]
	v_lshl_add_u64 v[12:13], s[52:53], 2, v[12:13]
	v_lshl_add_u64 v[12:13], v[12:13], 0, v[96:97]
	global_load_dwordx4 v[48:51], v[12:13], off nt
	s_and_b64 vcc, exec, s[0:1]
	v_mov_b32_e32 v122, v116
	s_cbranch_vccnz .LBB0_104
	v_mul_f32_e32 v122, v116, v159
.LBB0_104:
	v_or_b32_e32 v12, 24, v62
	v_mad_u64_u32 v[12:13], s[54:55], v12, s59, 0
	v_mov_b32_e32 v14, v13
	v_mad_u64_u32 v[14:15], s[54:55], v63, s59, v[14:15]
	v_mov_b32_e32 v13, v14
	v_lshl_add_u64 v[12:13], v[12:13], 2, s[50:51]
	v_lshl_add_u64 v[12:13], s[52:53], 2, v[12:13]
	v_lshl_add_u64 v[12:13], v[12:13], 0, v[96:97]
	global_load_dwordx4 v[40:43], v[12:13], off nt
	s_and_b64 vcc, exec, s[0:1]
	v_mov_b32_e32 v126, v116
	s_cbranch_vccnz .LBB0_106
	v_mul_f32_e32 v126, v116, v160
.LBB0_106:
	v_or_b32_e32 v12, 32, v62
	v_mad_u64_u32 v[12:13], s[54:55], v12, s59, 0
	v_mov_b32_e32 v14, v13
	v_mad_u64_u32 v[14:15], s[54:55], v63, s59, v[14:15]
	v_mov_b32_e32 v13, v14
	v_lshl_add_u64 v[12:13], v[12:13], 2, s[50:51]
	v_lshl_add_u64 v[12:13], s[52:53], 2, v[12:13]
	v_lshl_add_u64 v[12:13], v[12:13], 0, v[96:97]
	global_load_dwordx4 v[28:31], v[12:13], off nt
	s_and_b64 vcc, exec, s[0:1]
	v_mov_b32_e32 v128, v116
	s_cbranch_vccnz .LBB0_108
	v_mul_f32_e32 v128, v116, v161
.LBB0_108:
	v_or_b32_e32 v12, 40, v62
	v_mad_u64_u32 v[12:13], s[54:55], v12, s59, 0
	v_mov_b32_e32 v14, v13
	v_mad_u64_u32 v[14:15], s[54:55], v63, s59, v[14:15]
	v_mov_b32_e32 v13, v14
	v_lshl_add_u64 v[12:13], v[12:13], 2, s[50:51]
	v_lshl_add_u64 v[12:13], s[52:53], 2, v[12:13]
	v_lshl_add_u64 v[12:13], v[12:13], 0, v[96:97]
	global_load_dwordx4 v[20:23], v[12:13], off nt
	s_and_b64 vcc, exec, s[0:1]
	v_mov_b32_e32 v130, v116
	s_cbranch_vccnz .LBB0_110
	v_mul_f32_e32 v130, v116, v162
.LBB0_110:
	v_or_b32_e32 v12, 48, v62
	v_mad_u64_u32 v[12:13], s[54:55], v12, s59, 0
	v_mov_b32_e32 v14, v13
	v_mad_u64_u32 v[14:15], s[54:55], v63, s59, v[14:15]
	v_mov_b32_e32 v13, v14
	v_lshl_add_u64 v[12:13], v[12:13], 2, s[50:51]
	v_lshl_add_u64 v[12:13], s[52:53], 2, v[12:13]
	v_lshl_add_u64 v[12:13], v[12:13], 0, v[96:97]
	global_load_dwordx4 v[12:15], v[12:13], off nt
	s_and_b64 vcc, exec, s[0:1]
	s_cbranch_vccnz .LBB0_112
	v_mul_f32_e32 v116, v116, v163
